# hand-scheduled diff-attention (group A) loop: PV lagged one tile behind QK, 12-quad operand ring, fma bias from per-lane constants; plus v7 MLA loop
# speedup vs baseline: 1.0448x; 1.0448x over previous
; DEV void attn_a_item(const Params& P, int layer, int batch, int item, char* lds) {
;   const int tid = opaque_tid(), wid = tid >> 6, lane = tid & 63, r32 = lane & 31, hi = lane >> 5;
;   const int seqlen = batch ? 16384 : 4096;
;   const int head = 3 - (item >> 7), k_ = item & 127;
;   const int kk_ = batch ? k_ : (k_ >> 2), mid_ = batch ? 64 : 16;
;   const int qb = mid_ + ((kk_ & 1) ? -((kk_ + 1) >> 1) : (kk_ >> 1));
;   const int seq = batch ? 0 : (k_ & 3);
;   const long tok0 = (long)seq * 4096;
;   const int c = wid >> 2, wq = wid & 3;
;   const int qpos = qb * 128 + wq * 32 + r32;
;   char* V_lds = lds; char* K_lds = lds + 32768;
;   float* wsl = reinterpret_cast<float*>(lds + LDS_WS) + wid * 64;
;   const float lam = WS{P.ws}.consts()[layer * 1024 + 0], nMC = -WS{P.ws}.consts()[layer * 1024 + 1], lam_init = WS{P.ws}.consts()[layer * 1024 + 3];
;   const float nslope = -exp2f(-2.f * (float)(head + 1)) * LOG2E;
;   bf16x8 qr[4];
;   {
;     const u16* Qw = WS{P.ws}.QA() + (tok0 + qpos) * 512 + head * 128 + c * 64 + hi * 8;
; #pragma unroll
;     for (int ks = 0; ks < 4; ++ks) qr[ks] = *reinterpret_cast<const bf16x8*>(Qw + ks * 16);
;   }
;   const u16* Kh = WS{P.ws}.KA() + tok0 * 512 + head * 128;
;   const u16* Vh = WS{P.ws}.VA() + tok0 * 512 + head * 128;
;   int akoff[2], avoff[2], ldst[2];
; #pragma unroll
;   for (int i = 0; i < 2; ++i) {
;     const int p = (wid + 8 * i) * 1024 + lane * 16;
;     ldst[i] = p;
;     const int row = p >> 8, cB = (p & 255) ^ ((row & 7) << 4);
;     akoff[i] = row * 512 + (cB >> 1);
;     const int st = p >> 9, within = p & 511, kk = (st >> 2) * 8 + (within >> 6);
;     const int k = kk, col = (st & 3) * 32 + ((within & 63) >> 1);
;     avoff[i] = k * 512 + col;
;   }
;   const int vb0 = (int)(uintptr_t)V_lds + v_rd_base(lane);
;     ...
;   f32x16 o[4] = {f32x16{}, f32x16{}, f32x16{}, f32x16{}};
;   float lsum = 0.f;
;   const int NT = seqlen >> 6;
; DEV void phase_attn(const Params& P, int layer, int batch, char* lds) {
;     ...
;   for (;;) {
;     if (threadIdx.x == 0) *qw = (int)__hip_atomic_fetch_add(ctr, 1u, __ATOMIC_RELAXED, __HIP_MEMORY_SCOPE_AGENT);
;     __syncthreads();
;     const int it = __builtin_amdgcn_readfirstlane(*qw);
;     __syncthreads();
;     if (it >= 768) break;
;     if (it < 256) attn_b_item(P, layer, batch, it, lds);
;     else          attn_a_item(P, layer, batch, it - 256, lds);
.LBB0_371:
	s_or_b64 exec, exec, s[2:3]
	s_add_i32 s2, 0, 0x207f0
	s_cmp_lg_u32 s2, -1
	s_cselect_b32 s2, s2, 0
	s_cselect_b32 s3, s21, 0
	v_mov_b32_e32 v0, s2
	v_mov_b32_e32 v1, s3
	s_waitcnt lgkmcnt(0)
	s_barrier
	flat_load_dword v0, v[0:1] sc0 sc1
	s_waitcnt vmcnt(0)
	s_mov_b64 s[2:3], -1
	s_waitcnt lgkmcnt(0)
	s_barrier
	v_readfirstlane_b32 s63, v0
	s_cmpk_gt_i32 s63, 0x2ff
	s_cbranch_scc1 .LBB0_368
	s_cmpk_gt_i32 s63, 0xff
	s_cbranch_scc0 .LBB0_390
	s_add_i32 s22, s63, 0xffffff00
	s_and_b32 s18, s63, 0x7f
	s_bfe_u32 s19, s63, 0x50002
	s_and_b64 s[2:3], s[26:27], exec
	s_cselect_b32 s2, s19, s18
	s_add_i32 s18, s2, 1
	s_lshr_b32 s18, s18, 1
	s_and_b32 s3, s2, 1
	s_sub_i32 s18, 0, s18
	s_lshr_b32 s2, s2, 1
	s_cmp_eq_u32 s3, 0
	s_cselect_b32 s2, s2, s18
	v_readlane_b32 s3, v254, 32
	v_mov_b32_e32 v159, v226
	s_add_i32 s24, s2, s3
	s_lshl_b32 s2, s22, 12
	s_and_b32 s18, s2, 0x3000
	v_ashrrev_i32_e32 v4, 6, v159
	s_and_b64 s[2:3], s[26:27], exec
	v_lshlrev_b32_e32 v161, 5, v4
	v_and_b32_e32 v162, 31, v159
	s_cselect_b32 s19, 0, 0
	s_cselect_b32 s18, s18, 0
	s_lshl_b32 s64, s24, 7
	v_and_b32_e32 v163, 0x60, v161
	v_or3_b32 v0, v162, s64, v163
	s_lshr_b32 s2, s22, 6
	s_and_b32 s2, s2, 6
	v_ashrrev_i32_e32 v1, 31, v0
	s_or_b32 s2, s2, -8
	v_lshl_add_u64 v[0:1], s[18:19], 0, v[0:1]
	v_ashrrev_i32_e32 v164, 8, v159
	v_mov_b64_e32 v[2:3], s[8:9]
	v_ldexp_f32 v13, 1.0, s2
	v_lshlrev_b64 v[0:1], 10, v[0:1]
	s_andn2_b32 s2, 0x180, s22
	flat_load_dwordx2 v[128:129], v[2:3]
	flat_load_dword v158, v[2:3] offset:12
	v_lshl_add_u64 v[0:1], s[10:11], 0, v[0:1]
	s_lshl_b32 s22, s2, 1
	v_lshlrev_b32_e32 v2, 6, v164
	v_and_b32_e32 v165, 63, v159
	v_lshl_add_u64 v[0:1], v[0:1], 0, s[22:23]
	v_ashrrev_i32_e32 v3, 31, v2
	v_lshl_add_u64 v[0:1], v[2:3], 1, v[0:1]
	v_lshlrev_b32_e32 v6, 10, v4
	v_lshlrev_b32_e32 v3, 4, v165
	v_bfe_u32 v8, v159, 2, 3
	v_or_b32_e32 v166, v6, v3
	v_ashrrev_i32_e32 v4, 8, v6
	v_lshlrev_b32_e32 v11, 3, v165
	v_and_or_b32 v9, v4, s45, v8
	v_lshrrev_b32_e32 v5, 4, v166
	v_bfe_u32 v160, v159, 5, 1
	s_lshl_b32 s2, s18, 10
	v_and_b32_e32 v2, 24, v11
	v_and_b32_e32 v5, 0x60, v5
	v_lshlrev_b32_e32 v9, 9, v9
	v_lshlrev_b32_e32 v184, 4, v160
	s_add_u32 s24, s34, s2
	v_or3_b32 v14, v9, v5, v2
	v_add_u32_e32 v9, 0x2000, v6
	v_lshl_add_u64 v[0:1], v[0:1], 0, v[184:185]
	s_addc_u32 s25, s35, 0
	v_or_b32_e32 v15, v9, v3
	v_mul_f32_e32 v130, 0xbfb8aa3b, v13
	flat_load_dwordx4 v[96:99], v[0:1]
	flat_load_dwordx4 v[100:103], v[0:1] offset:32
	flat_load_dwordx4 v[104:107], v[0:1] offset:64
	flat_load_dwordx4 v[108:111], v[0:1] offset:96
	s_add_u32 s65, s36, s2
	v_ashrrev_i32_e32 v0, 8, v166
	v_ashrrev_i32_e32 v6, 8, v15
	v_div_scale_f32 v13, s[2:3], v130, v130, s46
	v_and_b32_e32 v7, 0xf0, v3
	v_lshlrev_b32_e32 v1, 4, v0
	v_lshlrev_b32_e32 v10, 4, v6
	v_rcp_f32_e32 v19, v13
	v_bitop3_b32 v1, v1, v7, s95 bitop3:0x6c
	v_bitop3_b32 v7, v10, v7, s95 bitop3:0x6c
	v_ashrrev_i32_e32 v10, 8, v9
	v_and_or_b32 v17, v10, s45, v8
	v_lshrrev_b32_e32 v15, 4, v15
	v_and_b32_e32 v15, 0x60, v15
	v_lshlrev_b32_e32 v17, 9, v17
	v_or3_b32 v18, v17, v15, v2
	v_fma_f32 v15, -v13, v19, 1.0
	v_fmac_f32_e32 v19, v15, v19
	v_div_scale_f32 v15, vcc, s46, v130, s46
	v_mul_f32_e32 v17, v15, v19
	v_fma_f32 v20, -v13, v17, v15
	v_fmac_f32_e32 v17, v20, v19
	v_fma_f32 v13, -v13, v17, v15
	v_div_fmas_f32 v13, v13, v19, v17
	v_div_fixup_f32 v13, v13, v130, s46
	v_min_f32_e32 v13, 0x49742400, v13
	v_cvt_i32_f32_e32 v13, v13
	s_addc_u32 s68, s38, 0
	s_add_u32 s3, s24, s22
	s_addc_u32 s71, s25, 0
	s_add_u32 s74, s65, s22
	v_readfirstlane_b32 s24, v13
	s_addc_u32 s75, s68, 0
	s_sub_i32 s2, s64, s24
	s_ashr_i32 s2, s2, 6
	s_or_b32 s65, s64, 0x7f
	s_max_i32 s2, s2, 0
	s_add_i32 s24, s65, s24
	s_ashr_i32 s78, s24, 6
	s_lshl_b32 s24, s2, 6
	s_mov_b32 s25, s23
	s_lshl_b64 s[68:69], s[24:25], 10
	v_lshlrev_b32_e32 v0, 9, v0
	v_lshrrev_b32_e32 v1, 1, v1
	s_add_u32 s70, s3, s68
	v_add_u32_e32 v20, 0, v166
	v_or_b32_e32 v12, v1, v0
	s_addc_u32 s71, s71, s69
	v_add_u32_e32 v15, 0x8000, v20
	s_add_u32 s68, s74, s68
	v_ashrrev_i32_e32 v13, 31, v12
	v_readfirstlane_b32 s3, v15
	v_lshlrev_b32_e32 v6, 9, v6
	v_lshrrev_b32_e32 v7, 1, v7
	s_addc_u32 s69, s75, s69
	v_lshl_add_u64 v[12:13], v[12:13], 1, s[70:71]
	s_mov_b32 m0, s3
	v_ashrrev_i32_e32 v15, 31, v14
	v_or_b32_e32 v16, v7, v6
	global_load_lds_dwordx4 v[12:13], off
	v_lshl_add_u64 v[12:13], v[14:15], 1, s[68:69]
	v_readfirstlane_b32 s3, v20
	v_add_u32_e32 v14, 0xa000, v20
	s_mov_b32 m0, s3
	v_ashrrev_i32_e32 v17, 31, v16
	v_readfirstlane_b32 s3, v14
	v_add_u32_e32 v14, 0x2000, v20
	global_load_lds_dwordx4 v[12:13], off
	v_lshl_add_u64 v[12:13], v[16:17], 1, s[70:71]
	s_mov_b32 m0, s3
	v_ashrrev_i32_e32 v19, 31, v18
	v_readfirstlane_b32 s3, v14
	global_load_lds_dwordx4 v[12:13], off
	v_lshl_add_u64 v[12:13], v[18:19], 1, s[68:69]
	s_mov_b32 m0, s3
	s_min_i32 s70, s49, s78
	global_load_lds_dwordx4 v[12:13], off
	s_waitcnt vmcnt(0)
	s_mov_b32 s25, 0
	s_cmp_gt_i32 s2, s70
	s_waitcnt vmcnt(0) lgkmcnt(0)
	s_barrier
	s_cbranch_scc1 .LBB0_382
; DEV int v_rd_base(int lane) { return ((lane & 3) << 3) | (((lane >> 2) & 3) << 6) | (((lane >> 4) & 1) << 5) | (((lane >> 5) & 1) << 8); }
; #define ALOAD(b, k0) do { _Pragma("unroll") for (int i = 0; i < 2; ++i) { glds16(Kh + (long)(k0) * 512 + akoff[i], K_lds + (b) * 16384 + ldst[i]); \
;     glds16(Vh + (long)(k0) * 512 + avoff[i], V_lds + (b) * 16384 + ldst[i]); } } while (0)
; DEV void attn_a_item(const Params& P, int layer, int batch, int item, char* lds) {
;     ...
;   const int vb0 = (int)(uintptr_t)V_lds + v_rd_base(lane);
;     ...
;   f32x16 o[4] = {f32x16{}, f32x16{}, f32x16{}, f32x16{}};
;   float lsum = 0.f;
;   const int NT = seqlen >> 6;
;   const int Dk = (int)fminf(160.f / -nslope, 1.0e6f);
;   const int jlo = max(0, (qb * 128 - Dk) >> 6), jhi = min(NT - 1, (qb * 128 + 127 + Dk) >> 6);
;   ALOAD(0, jlo * 64); asm volatile("s_waitcnt vmcnt(0)" ::: "memory"); __syncthreads();
;   for (int j = jlo; j <= jhi; ++j) {
;     const int bcur = (j - jlo) & 1;
;     const char* Ks = K_lds + bcur * 16384;
;     f32x16 p0, p1;
;     {
;       const float dbase = (float)(j * 64 - qpos + 4 * hi);
;       const int q0 = qb * 128;
;       if (j * 64 + 63 < q0 || j * 64 > q0 + 127) {
;         const float step = (j * 64 < q0) ? -nslope : nslope;
;         const float base = fmaf(dbase, step, nMC), step8 = 8.f * step;
;         p0[0] = base; p0[1] = base + step; p0[2] = fmaf(2.f, step, base); p0[3] = fmaf(3.f, step, base);
; #pragma unroll
;         for (int r = 4; r < 16; ++r) p0[r] = p0[r - 4] + step8;
; #pragma unroll
;         for (int r = 0; r < 4; ++r) p1[r] = p0[r + 12] + step8;
; #pragma unroll
;         for (int r = 4; r < 16; ++r) p1[r] = p1[r - 4] + step8;
;       } else {
;         float d0[16], d1[16];
;         d0[0] = dbase; d0[1] = dbase + 1.f; d0[2] = dbase + 2.f; d0[3] = d0[1] + 2.f;
; #pragma unroll
;         for (int r = 4; r < 16; ++r) d0[r] = d0[r - 4] + 8.f;
; #pragma unroll
;         for (int r = 0; r < 4; ++r) d1[r] = d0[r + 12] + 8.f;
; #pragma unroll
;         for (int r = 4; r < 16; ++r) d1[r] = d1[r - 4] + 8.f;
; #pragma unroll
;         for (int r = 0; r < 16; ++r) { p0[r] = fmaf(fabsf(d0[r]), nslope, nMC); p1[r] = fmaf(fabsf(d1[r]), nslope, nMC); }
;       }
;     }
;     const int vb = vb0 + bcur * 16384;
	s_cmp_lg_u32 0, -1
	v_and_b32_e32 v13, 0xc0, v3
	s_cselect_b32 s3, 0, 0
	v_lshlrev_b32_e32 v12, 1, v165
	v_add_u32_e32 v13, s3, v13
	s_mov_b32 s3, s23
	v_and_b32_e32 v12, 32, v12
	v_and_b32_e32 v11, 0x118, v11
	s_lshl_b64 s[68:69], s[2:3], 16
	s_lshl_b64 s[74:75], s[18:19], 10
	v_add_u32_e32 v3, v9, v3
	v_add3_u32 v173, v13, v12, v11
	s_add_u32 s3, s68, s74
	v_lshlrev_b32_e32 v10, 9, v10
	v_lshlrev_b32_e32 v11, 9, v8
	s_movk_i32 s74, 0xf000
	v_lshrrev_b32_e32 v3, 4, v3
	v_and_or_b32 v8, v10, s74, v11
	v_and_b32_e32 v3, 0x60, v3
	v_or3_b32 v8, v8, v3, v2
	v_lshlrev_b32_e32 v3, 9, v4
	s_addc_u32 s71, s69, s75
	v_and_or_b32 v3, v3, s74, v11
	s_add_u32 s68, s55, s3
	v_or3_b32 v2, v3, v5, v2
	v_ashrrev_i32_e32 v9, 31, v8
	s_addc_u32 s69, s60, s71
	v_ashrrev_i32_e32 v3, 31, v2
	v_lshl_add_u64 v[150:151], v[8:9], 1, s[68:69]
	v_lshl_add_u64 v[152:153], v[2:3], 1, s[68:69]
	s_add_u32 s68, s61, s3
	v_add_u32_e32 v0, v1, v0
	v_lshlrev_b32_e32 v14, 2, v160
	s_addc_u32 s69, s62, s71
	v_ashrrev_i32_e32 v1, 31, v0
	v_lshlrev_b32_e32 v15, 7, v164
	v_lshlrev_b32_e32 v17, 4, v159
	v_add_u32_e32 v2, v7, v6
	v_lshl_add_u64 v[156:157], v[0:1], 1, s[68:69]
	v_sub_u32_e32 v0, v14, v162
	v_or_b32_e32 v16, v184, v15
	v_and_b32_e32 v17, 0x70, v17
	v_xor_b32_e32 v132, 0x80000000, v129
	v_ashrrev_i32_e32 v3, 31, v2
	v_sub_u32_e32 v0, v0, v163
	v_mov_b32_e32 v167, 0
	v_lshl_add_u32 v168, v162, 8, 0
	v_bitop3_b32 v169, v184, v17, v15 bitop3:0x36
	v_bitop3_b32 v170, v16, v17, 32 bitop3:0x36
	v_bitop3_b32 v171, v16, v17, 64 bitop3:0x36
	v_bitop3_b32 v172, v16, v17, s56 bitop3:0x36
	v_mov_b32_e32 v134, v130
	v_mov_b32_e32 v135, v130
	v_mov_b32_e32 v133, v132
	v_mov_b32_e32 v136, v132
	v_mov_b32_e32 v137, v132
	v_mov_b32_e32 v138, v132
	v_mov_b32_e32 v139, v132
	v_mov_b32_e32 v140, v132
	v_mov_b32_e32 v141, v132
	v_mov_b32_e32 v142, v132
	v_mov_b32_e32 v143, v132
	v_mov_b32_e32 v144, v132
	v_mov_b32_e32 v145, v132
	v_mov_b32_e32 v146, v132
	v_mov_b32_e32 v147, v132
	v_mov_b32_e32 v148, v132
	v_mov_b32_e32 v149, v132
	v_lshl_add_u64 v[154:155], v[2:3], 1, s[68:69]
	v_subrev_u32_e32 v174, s64, v0
	v_mov_b32_e32 v48, 0
	v_mov_b32_e32 v49, v167
	v_mov_b32_e32 v50, v167
	v_mov_b32_e32 v51, v167
	v_mov_b32_e32 v52, v167
	v_mov_b32_e32 v53, v167
	v_mov_b32_e32 v54, v167
	v_mov_b32_e32 v55, v167
	v_mov_b32_e32 v56, v167
	v_mov_b32_e32 v57, v167
	v_mov_b32_e32 v58, v167
	v_mov_b32_e32 v59, v167
	v_mov_b32_e32 v60, v167
	v_mov_b32_e32 v61, v167
	v_mov_b32_e32 v62, v167
	v_mov_b32_e32 v63, v167
	v_mov_b32_e32 v32, 0
	v_mov_b32_e32 v33, v167
	v_mov_b32_e32 v34, v167
	v_mov_b32_e32 v35, v167
	v_mov_b32_e32 v36, v167
	v_mov_b32_e32 v37, v167
	v_mov_b32_e32 v38, v167
	v_mov_b32_e32 v39, v167
	v_mov_b32_e32 v40, v167
	v_mov_b32_e32 v41, v167
	v_mov_b32_e32 v42, v167
	v_mov_b32_e32 v43, v167
	v_mov_b32_e32 v44, v167
	v_mov_b32_e32 v45, v167
	v_mov_b32_e32 v46, v167
	v_mov_b32_e32 v47, v167
	v_mov_b32_e32 v16, 0
	v_mov_b32_e32 v17, v167
	v_mov_b32_e32 v18, v167
	v_mov_b32_e32 v19, v167
	v_mov_b32_e32 v20, v167
	v_mov_b32_e32 v21, v167
	v_mov_b32_e32 v22, v167
	v_mov_b32_e32 v23, v167
	v_mov_b32_e32 v24, v167
	v_mov_b32_e32 v25, v167
	v_mov_b32_e32 v26, v167
	v_mov_b32_e32 v27, v167
	v_mov_b32_e32 v28, v167
	v_mov_b32_e32 v29, v167
	v_mov_b32_e32 v30, v167
	v_mov_b32_e32 v31, v167
	v_mov_b32_e32 v0, 0
	v_mov_b32_e32 v1, v167
	v_mov_b32_e32 v2, v167
	v_mov_b32_e32 v3, v167
	v_mov_b32_e32 v4, v167
	v_mov_b32_e32 v5, v167
	v_mov_b32_e32 v6, v167
	v_mov_b32_e32 v7, v167
	v_mov_b32_e32 v8, v167
	v_mov_b32_e32 v9, v167
	v_mov_b32_e32 v10, v167
	v_mov_b32_e32 v11, v167
	v_mov_b32_e32 v12, v167
	v_mov_b32_e32 v13, v167
	v_mov_b32_e32 v14, v167
	v_mov_b32_e32 v15, v167
	v_add_u32_e32 v169, v168, v169
	v_add_u32_e32 v170, v168, v170
	v_add_u32_e32 v171, v168, v171
	v_add_u32_e32 v172, v168, v172
	v_add_u32_e32 v169, 0x8000, v169
	v_add_u32_e32 v170, 0x8000, v170
	v_add_u32_e32 v171, 0x8000, v171
	v_add_u32_e32 v172, 0x8000, v172
	v_readfirstlane_b32 s100, v166
	v_readfirstlane_b32 s25, v130
	v_cvt_f32_i32_e32 v166, v174
	s_nop 0
	v_mov_b32_e32 v112, v166
	v_add_f32_e32 v113, 0x3f800000, v166
	v_add_f32_e32 v114, 0x40000000, v166
	v_add_f32_e32 v115, 0x40400000, v166
	v_add_f32_e32 v116, 0x41000000, v166
	v_add_f32_e32 v117, 0x41100000, v166
	v_add_f32_e32 v118, 0x41200000, v166
	v_add_f32_e32 v119, 0x41300000, v166
	v_add_f32_e32 v120, 0x41800000, v166
	v_add_f32_e32 v121, 0x41880000, v166
	v_add_f32_e32 v122, 0x41900000, v166
	v_add_f32_e32 v123, 0x41980000, v166
	v_add_f32_e32 v124, 0x41c00000, v166
	v_add_f32_e32 v125, 0x41c80000, v166
	v_add_f32_e32 v126, 0x41d00000, v166
	v_add_f32_e32 v127, 0x41d80000, v166
	v_add_f32_e32 v133, 0x42000000, v166
	v_add_f32_e32 v134, 0x42040000, v166
	v_add_f32_e32 v135, 0x42080000, v166
	v_add_f32_e32 v136, 0x420c0000, v166
	v_add_f32_e32 v137, 0x42200000, v166
	v_add_f32_e32 v138, 0x42240000, v166
	v_add_f32_e32 v139, 0x42280000, v166
	v_add_f32_e32 v140, 0x422c0000, v166
	v_add_f32_e32 v141, 0x42400000, v166
	v_add_f32_e32 v142, 0x42440000, v166
	v_add_f32_e32 v143, 0x42480000, v166
	v_add_f32_e32 v144, 0x424c0000, v166
	v_add_f32_e32 v145, 0x42600000, v166
	v_add_f32_e32 v146, 0x42640000, v166
	v_add_f32_e32 v147, 0x42680000, v166
	v_add_f32_e32 v148, 0x426c0000, v166
	v_readfirstlane_b32 s71, v156
	v_readfirstlane_b32 s101, v157
	s_nop 3
	s_sub_u32 s71, s71, 0x1000
	s_subb_u32 s101, s101, 0
	v_subrev_u32_e32 v174, s71, v156
	v_subrev_u32_e32 v175, s71, v154
	s_add_u32 s68, s71, s22
	s_addc_u32 s69, s101, 0
	v_readfirstlane_b32 s71, v152
	v_readfirstlane_b32 s101, v153
	s_nop 3
	s_sub_u32 s71, s71, 0x1000
	s_subb_u32 s101, s101, 0
	v_subrev_u32_e32 v149, s71, v152
	v_subrev_u32_e32 v131, s71, v150
	s_add_u32 s74, s71, s22
	s_addc_u32 s75, s101, 0
	s_xor_b32 s65, s25, 0x80000000
	s_lshr_b32 s78, s64, 6
	v_mov_b32_e32 v154, 0
	v_mov_b32_e32 v155, 0
	v_mov_b32_e32 v156, 0
	v_mov_b32_e32 v157, 0
	v_mov_b32_e32 v202, 0
	v_mov_b32_e32 v203, 0
	v_mov_b32_e32 v204, 0
	v_mov_b32_e32 v205, 0
	v_mov_b32_e32 v206, 0
	v_mov_b32_e32 v207, 0
	v_mov_b32_e32 v208, 0
	v_mov_b32_e32 v209, 0
	v_mov_b32_e32 v210, 0
	v_mov_b32_e32 v211, 0
	v_mov_b32_e32 v212, 0
	v_mov_b32_e32 v213, 0
	v_mov_b32_e32 v214, 0
	v_mov_b32_e32 v215, 0
	v_mov_b32_e32 v216, 0
	v_mov_b32_e32 v217, 0
	s_cmp_lt_i32 s2, s78
	s_cselect_b32 s3, s65, s25
	s_sub_u32 s71, s2, s78
	s_cmp_lt_u32 s71, 2
	s_cselect_b64 vcc, -1, 0
	v_cvt_f32_i32_e32 v129, s24
	s_nop 0
	v_fma_f32 v168, v129, s3, v132
	ds_read_b128 v[218:221], v169 offset:0
	ds_read_b128 v[222:225], v170 offset:0
	ds_read_b128 v[232:235], v171 offset:0
	ds_read_b128 v[236:239], v172 offset:0
	ds_read_b128 v[240:243], v169 offset:8192
	ds_read_b128 v[244:247], v170 offset:8192
	ds_read_b128 v[248:251], v171 offset:8192
	ds_read_b128 v[194:197], v172 offset:8192
	s_cbranch_vccnz .Ldfa_diag_f_a
; DEV void attn_a_item(const Params& P, int layer, int batch, int item, char* lds) {
;     ...
;     f32x16 p0, p1;
;     {
;       const float dbase = (float)(j * 64 - qpos + 4 * hi);
;       const int q0 = qb * 128;
;       if (j * 64 + 63 < q0 || j * 64 > q0 + 127) {
;         const float step = (j * 64 < q0) ? -nslope : nslope;
;         const float base = fmaf(dbase, step, nMC), step8 = 8.f * step;
;         p0[0] = base; p0[1] = base + step; p0[2] = fmaf(2.f, step, base); p0[3] = fmaf(3.f, step, base);
; #pragma unroll
;         for (int r = 4; r < 16; ++r) p0[r] = p0[r - 4] + step8;
; #pragma unroll
;         for (int r = 0; r < 4; ++r) p1[r] = p0[r + 12] + step8;
; #pragma unroll
;         for (int r = 4; r < 16; ++r) p1[r] = p1[r - 4] + step8;
;       } else {
;         float d0[16], d1[16];
;         d0[0] = dbase; d0[1] = dbase + 1.f; d0[2] = dbase + 2.f; d0[3] = d0[1] + 2.f;
; #pragma unroll
;         for (int r = 4; r < 16; ++r) d0[r] = d0[r - 4] + 8.f;
; #pragma unroll
;         for (int r = 0; r < 4; ++r) d1[r] = d0[r + 12] + 8.f;
; #pragma unroll
;         for (int r = 4; r < 16; ++r) d1[r] = d1[r - 4] + 8.f;
; #pragma unroll
;         for (int r = 0; r < 16; ++r) { p0[r] = fmaf(fabsf(d0[r]), nslope, nMC); p1[r] = fmaf(fabsf(d1[r]), nslope, nMC); }
;       }
;     }
;     const int vb = vb0 + bcur * 16384;
;     bf16x8 pa0, pa1, pa2, pa3;
;     s16x4 fa[8], fb[8];
;     bf16x8 kf[8];
; #pragma unroll
;     for (int ks = 0; ks < 4; ++ks) {
;       const int cb = c * 128 + (ks * 16 + hi * 8) * 2;
;       kf[2 * ks] = *reinterpret_cast<const bf16x8*>(Ks + KSWZ(r32, cb));
;       kf[2 * ks + 1] = *reinterpret_cast<const bf16x8*>(Ks + KSWZ(32 + r32, cb));
;     }
; #pragma unroll
;     for (int ks = 0; ks < 4; ++ks) p0 = __builtin_amdgcn_mfma_f32_32x32x16_bf16(kf[2 * ks], qr[ks], p0, 0, 0, 0);
;     SBAR();
;     if (j + 1 <= jhi) ALOAD(bcur ^ 1, (j + 1) * 64);
;     SBAR();
;     trq<0, 0>(vb, fa);
; #pragma unroll
;     for (int ks = 0; ks < 4; ++ks) p1 = __builtin_amdgcn_mfma_f32_32x32x16_bf16(kf[2 * ks + 1], qr[ks], p1, 0, 0, 0);
;     sm_exp(p0, lsum); sm_pack(p0, pa0, pa1);
;     asm volatile("s_waitcnt lgkmcnt(0)" ::: "memory"); SBAR();
;     trq<0, 2>(vb, fb);
;     mmaq(o[0], o[1], fa, pa0, pa1);
;     sm_exp(p1, lsum);
;     asm volatile("s_waitcnt lgkmcnt(0)" ::: "memory"); SBAR();
;     trq<2, 0>(vb, fa);
;     mmaq(o[2], o[3], fb, pa0, pa1);
	v_fma_f32 v64, v112, s3, v168
	v_fma_f32 v65, v113, s3, v168
	v_fma_f32 v66, v114, s3, v168
	v_fma_f32 v67, v115, s3, v168
	v_fma_f32 v68, v116, s3, v168
	v_fma_f32 v69, v117, s3, v168
	v_fma_f32 v70, v118, s3, v168
	v_fma_f32 v71, v119, s3, v168
	v_fma_f32 v72, v120, s3, v168
	v_fma_f32 v73, v121, s3, v168
	v_fma_f32 v74, v122, s3, v168
	v_fma_f32 v75, v123, s3, v168
	v_fma_f32 v76, v124, s3, v168
	v_fma_f32 v77, v125, s3, v168
	v_fma_f32 v78, v126, s3, v168
	v_fma_f32 v79, v127, s3, v168
.Ldfa_back_f_a:
	s_cbranch_vccnz .Ldfa_diag_f_b
	v_fma_f32 v80, v133, s3, v168
	v_fma_f32 v81, v134, s3, v168
	v_fma_f32 v82, v135, s3, v168
	v_fma_f32 v83, v136, s3, v168
	v_fma_f32 v84, v137, s3, v168
	v_fma_f32 v85, v138, s3, v168
	v_fma_f32 v86, v139, s3, v168
	v_fma_f32 v87, v140, s3, v168
	v_fma_f32 v88, v141, s3, v168
	v_fma_f32 v89, v142, s3, v168
	v_fma_f32 v90, v143, s3, v168
	v_fma_f32 v91, v144, s3, v168
	v_fma_f32 v92, v145, s3, v168
	v_fma_f32 v93, v146, s3, v168
	v_fma_f32 v94, v147, s3, v168
	v_fma_f32 v95, v148, s3, v168
.Ldfa_back_f_b:
	s_cmp_ge_i32 s2, s70
	s_cbranch_scc1 .Ldfa_skipk_f
	s_add_u32 m0, s100, 0xc000
	s_nop 0
	global_load_lds_dwordx4 v174, s[68:69]
	s_add_u32 m0, s100, 0xe000
	s_nop 0
	global_load_lds_dwordx4 v175, s[68:69]
	s_add_u32 s68, s68, 0x10000
	s_addc_u32 s69, s69, 0
.Ldfa_skipk_f:
	s_waitcnt lgkmcnt(7)
	v_mfma_f32_32x32x16_bf16 v[64:79], v[218:221], v[96:99], v[64:79]
	s_waitcnt lgkmcnt(6)
	v_mfma_f32_32x32x16_bf16 v[64:79], v[222:225], v[100:103], v[64:79]
	s_waitcnt lgkmcnt(5)
	v_mfma_f32_32x32x16_bf16 v[64:79], v[232:235], v[104:107], v[64:79]
	s_waitcnt lgkmcnt(4)
	v_mfma_f32_32x32x16_bf16 v[64:79], v[236:239], v[108:111], v[64:79]
	s_waitcnt lgkmcnt(3)
	v_mfma_f32_32x32x16_bf16 v[80:95], v[240:243], v[96:99], v[80:95]
	s_waitcnt lgkmcnt(2)
	v_mfma_f32_32x32x16_bf16 v[80:95], v[244:247], v[100:103], v[80:95]
	s_waitcnt lgkmcnt(1)
	v_mfma_f32_32x32x16_bf16 v[80:95], v[248:251], v[104:107], v[80:95]
	s_waitcnt lgkmcnt(0)
	v_mfma_f32_32x32x16_bf16 v[80:95], v[194:197], v[108:111], v[80:95]
	s_nop 7
	s_nop 7
	v_exp_f32_e32 v64, v64
	v_exp_f32_e32 v65, v65
	v_exp_f32_e32 v66, v66
	v_exp_f32_e32 v67, v67
	v_exp_f32_e32 v68, v68
	v_exp_f32_e32 v69, v69
	v_exp_f32_e32 v70, v70
	v_exp_f32_e32 v71, v71
	v_exp_f32_e32 v72, v72
	v_exp_f32_e32 v73, v73
	v_exp_f32_e32 v74, v74
	v_exp_f32_e32 v75, v75
	v_exp_f32_e32 v76, v76
	v_exp_f32_e32 v77, v77
	v_exp_f32_e32 v78, v78
	v_exp_f32_e32 v79, v79
	v_add_f32_e32 v167, v167, v64
	v_add_f32_e32 v167, v167, v65
	v_add_f32_e32 v167, v167, v66
	v_add_f32_e32 v167, v167, v67
	v_add_f32_e32 v167, v167, v68
	v_add_f32_e32 v167, v167, v69
	v_add_f32_e32 v167, v167, v70
	v_add_f32_e32 v167, v167, v71
	v_add_f32_e32 v167, v167, v72
	v_add_f32_e32 v167, v167, v73
	v_add_f32_e32 v167, v167, v74
	v_add_f32_e32 v167, v167, v75
	v_add_f32_e32 v167, v167, v76
	v_add_f32_e32 v167, v167, v77
	v_add_f32_e32 v167, v167, v78
	v_add_f32_e32 v167, v167, v79
	v_cvt_pk_bf16_f32 v176, v64, v65
	v_cvt_pk_bf16_f32 v177, v66, v67
	v_cvt_pk_bf16_f32 v178, v68, v69
	v_cvt_pk_bf16_f32 v179, v70, v71
	v_cvt_pk_bf16_f32 v180, v72, v73
	v_cvt_pk_bf16_f32 v181, v74, v75
	v_cvt_pk_bf16_f32 v182, v76, v77
	v_cvt_pk_bf16_f32 v183, v78, v79
	v_exp_f32_e32 v80, v80
	v_exp_f32_e32 v81, v81
	v_exp_f32_e32 v82, v82
	v_exp_f32_e32 v83, v83
	v_exp_f32_e32 v84, v84
	v_exp_f32_e32 v85, v85
	v_exp_f32_e32 v86, v86
	v_exp_f32_e32 v87, v87
	v_exp_f32_e32 v88, v88
	v_exp_f32_e32 v89, v89
	v_exp_f32_e32 v90, v90
	v_exp_f32_e32 v91, v91
	v_exp_f32_e32 v92, v92
	v_exp_f32_e32 v93, v93
	v_exp_f32_e32 v94, v94
	v_exp_f32_e32 v95, v95
	s_nop 0
	v_cvt_pk_bf16_f32 v186, v80, v81
	v_cvt_pk_bf16_f32 v187, v82, v83
	v_cvt_pk_bf16_f32 v188, v84, v85
	v_cvt_pk_bf16_f32 v189, v86, v87
	v_cvt_pk_bf16_f32 v150, v88, v89
	v_cvt_pk_bf16_f32 v151, v90, v91
	v_cvt_pk_bf16_f32 v152, v92, v93
	v_cvt_pk_bf16_f32 v153, v94, v95
	s_waitcnt lgkmcnt(0)
	s_waitcnt vmcnt(0)
	s_barrier
	s_cmp_ge_i32 s2, s70
	s_cbranch_scc1 .Ldfa_drain0_pre
	s_add_u32 s2, s2, 1
	s_add_u32 s24, s24, 64
.Ldfa_loop:
	s_cmp_lt_i32 s2, s78
	s_cselect_b32 s3, s65, s25
	s_sub_u32 s71, s2, s78
	s_cmp_lt_u32 s71, 2
	s_cselect_b64 vcc, -1, 0
	v_cvt_f32_i32_e32 v129, s24
	s_nop 0
	v_fma_f32 v168, v129, s3, v132
	ds_read_b128 v[218:221], v169 offset:16384
	ds_read_b128 v[222:225], v170 offset:16384
	ds_read_b128 v[232:235], v171 offset:16384
	ds_read_b128 v[236:239], v172 offset:16384
	v_mfma_f32_32x32x16_bf16 v[48:63], v[154:157], v[202:205], v[48:63]
	ds_read_b64_tr_b16 v[240:241], v173 offset:0
	ds_read_b64_tr_b16 v[242:243], v173 offset:2048
	s_cbranch_vccnz .Ldfa_diag_o_a
	v_fma_f32 v64, v112, s3, v168
	v_fma_f32 v65, v113, s3, v168
	v_fma_f32 v66, v114, s3, v168
	v_fma_f32 v67, v115, s3, v168
	v_fma_f32 v68, v116, s3, v168
	v_fma_f32 v69, v117, s3, v168
	v_fma_f32 v70, v118, s3, v168
	v_fma_f32 v71, v119, s3, v168
.Ldfa_back_o_a:
	v_mfma_f32_32x32x16_bf16 v[32:47], v[154:157], v[206:209], v[32:47]
	ds_read_b64_tr_b16 v[244:245], v173 offset:512
	ds_read_b64_tr_b16 v[246:247], v173 offset:2560
	v_mfma_f32_32x32x16_bf16 v[16:31], v[154:157], v[210:213], v[16:31]
	ds_read_b64_tr_b16 v[248:249], v173 offset:1024
	ds_read_b64_tr_b16 v[250:251], v173 offset:3072
	s_cbranch_vccnz .Ldfa_diag_o_b
	v_fma_f32 v72, v120, s3, v168
	v_fma_f32 v73, v121, s3, v168
	v_fma_f32 v74, v122, s3, v168
	v_fma_f32 v75, v123, s3, v168
	v_fma_f32 v76, v124, s3, v168
	v_fma_f32 v77, v125, s3, v168
	v_fma_f32 v78, v126, s3, v168
	v_fma_f32 v79, v127, s3, v168
; #define SBAR() __builtin_amdgcn_sched_barrier(0)
; #define ALOAD(b, k0) do { _Pragma("unroll") for (int i = 0; i < 2; ++i) { glds16(Kh + (long)(k0) * 512 + akoff[i], K_lds + (b) * 16384 + ldst[i]); \
;     glds16(Vh + (long)(k0) * 512 + avoff[i], V_lds + (b) * 16384 + ldst[i]); } } while (0)
; DEV void attn_a_item(const Params& P, int layer, int batch, int item, char* lds) {
;     ...
;     const int vb = vb0 + bcur * 16384;
;     bf16x8 pa0, pa1, pa2, pa3;
;     s16x4 fa[8], fb[8];
;     bf16x8 kf[8];
; #pragma unroll
;     for (int ks = 0; ks < 4; ++ks) {
;       const int cb = c * 128 + (ks * 16 + hi * 8) * 2;
;       kf[2 * ks] = *reinterpret_cast<const bf16x8*>(Ks + KSWZ(r32, cb));
;       kf[2 * ks + 1] = *reinterpret_cast<const bf16x8*>(Ks + KSWZ(32 + r32, cb));
;     }
; #pragma unroll
;     for (int ks = 0; ks < 4; ++ks) p0 = __builtin_amdgcn_mfma_f32_32x32x16_bf16(kf[2 * ks], qr[ks], p0, 0, 0, 0);
;     SBAR();
;     if (j + 1 <= jhi) ALOAD(bcur ^ 1, (j + 1) * 64);
;     SBAR();
;     trq<0, 0>(vb, fa);
; #pragma unroll
;     for (int ks = 0; ks < 4; ++ks) p1 = __builtin_amdgcn_mfma_f32_32x32x16_bf16(kf[2 * ks + 1], qr[ks], p1, 0, 0, 0);
;     sm_exp(p0, lsum); sm_pack(p0, pa0, pa1);
;     asm volatile("s_waitcnt lgkmcnt(0)" ::: "memory"); SBAR();
;     trq<0, 2>(vb, fb);
;     mmaq(o[0], o[1], fa, pa0, pa1);
;     sm_exp(p1, lsum);
;     asm volatile("s_waitcnt lgkmcnt(0)" ::: "memory"); SBAR();
;     trq<2, 0>(vb, fa);
;     mmaq(o[2], o[3], fb, pa0, pa1);
;     sm_pack(p1, pa2, pa3);
;     asm volatile("s_waitcnt lgkmcnt(0)" ::: "memory"); SBAR();
;     trq<2, 2>(vb, fb);
;     mmaq(o[0], o[1], fa, pa2, pa3);
;     asm volatile("s_waitcnt lgkmcnt(0)" ::: "memory"); SBAR();
;     mmaq(o[2], o[3], fb, pa2, pa3);
;     asm volatile("s_waitcnt vmcnt(0)" ::: "memory");
;     __syncthreads();
;   }
.Ldfa_back_o_b:
	v_mfma_f32_32x32x16_bf16 v[0:15], v[154:157], v[214:217], v[0:15]
	ds_read_b64_tr_b16 v[194:195], v173 offset:1536
	ds_read_b64_tr_b16 v[196:197], v173 offset:3584
	s_waitcnt lgkmcnt(11)
	v_mfma_f32_32x32x16_bf16 v[64:79], v[218:221], v[96:99], v[64:79]
	ds_read_b128 v[202:205], v169 offset:24576
	v_add_f32_e32 v167, v167, v80
	v_add_f32_e32 v167, v167, v81
	v_add_f32_e32 v167, v167, v82
	v_add_f32_e32 v167, v167, v83
	s_waitcnt lgkmcnt(11)
	v_mfma_f32_32x32x16_bf16 v[64:79], v[222:225], v[100:103], v[64:79]
	ds_read_b128 v[206:209], v170 offset:24576
	v_add_f32_e32 v167, v167, v84
	v_add_f32_e32 v167, v167, v85
	v_add_f32_e32 v167, v167, v86
	v_add_f32_e32 v167, v167, v87
	s_add_u32 m0, s100, 0x4000
	s_nop 0
	global_load_lds_dwordx4 v149, s[74:75]
	s_add_u32 m0, s100, 0x6000
	s_nop 0
	global_load_lds_dwordx4 v131, s[74:75]
	s_add_u32 s74, s74, 0x10000
	s_addc_u32 s75, s75, 0
	s_cmp_ge_i32 s2, s70
	s_cbranch_scc1 .Ldfa_skipk_o
	s_add_u32 m0, s100, 0x8000
	s_nop 0
	global_load_lds_dwordx4 v174, s[68:69]
	s_add_u32 m0, s100, 0xa000
	s_nop 0
	global_load_lds_dwordx4 v175, s[68:69]
	s_add_u32 s68, s68, 0x10000
	s_addc_u32 s69, s69, 0
.Ldfa_skipk_o:
	s_waitcnt lgkmcnt(11)
	v_mfma_f32_32x32x16_bf16 v[64:79], v[232:235], v[104:107], v[64:79]
	ds_read_b128 v[210:213], v171 offset:24576
	v_add_f32_e32 v167, v167, v88
	v_add_f32_e32 v167, v167, v89
	v_add_f32_e32 v167, v167, v90
	v_add_f32_e32 v167, v167, v91
	s_waitcnt lgkmcnt(11)
	v_mfma_f32_32x32x16_bf16 v[64:79], v[236:239], v[108:111], v[64:79]
	ds_read_b128 v[214:217], v172 offset:24576
	v_add_f32_e32 v167, v167, v92
	v_add_f32_e32 v167, v167, v93
	v_add_f32_e32 v167, v167, v94
	v_add_f32_e32 v167, v167, v95
	s_waitcnt lgkmcnt(10)
	v_mfma_f32_32x32x16_bf16 v[48:63], v[176:179], v[240:243], v[48:63]
	ds_read_b64_tr_b16 v[218:219], v173 offset:4096
	ds_read_b64_tr_b16 v[220:221], v173 offset:6144
	s_cbranch_vccnz .Ldfa_diag_o_c
	v_fma_f32 v80, v133, s3, v168
	v_fma_f32 v81, v134, s3, v168
	v_fma_f32 v82, v135, s3, v168
	v_fma_f32 v83, v136, s3, v168
	v_fma_f32 v84, v137, s3, v168
	v_fma_f32 v85, v138, s3, v168
	v_fma_f32 v86, v139, s3, v168
	v_fma_f32 v87, v140, s3, v168
.Ldfa_back_o_c:
	s_waitcnt lgkmcnt(10)
	v_mfma_f32_32x32x16_bf16 v[32:47], v[176:179], v[244:247], v[32:47]
	ds_read_b64_tr_b16 v[222:223], v173 offset:4608
	ds_read_b64_tr_b16 v[224:225], v173 offset:6656
	s_cbranch_vccnz .Ldfa_diag_o_d
	v_fma_f32 v88, v141, s3, v168
	v_fma_f32 v89, v142, s3, v168
	v_fma_f32 v90, v143, s3, v168
	v_fma_f32 v91, v144, s3, v168
	v_fma_f32 v92, v145, s3, v168
	v_fma_f32 v93, v146, s3, v168
	v_fma_f32 v94, v147, s3, v168
	v_fma_f32 v95, v148, s3, v168
.Ldfa_back_o_d:
	s_waitcnt lgkmcnt(10)
	v_mfma_f32_32x32x16_bf16 v[16:31], v[176:179], v[248:251], v[16:31]
	ds_read_b64_tr_b16 v[232:233], v173 offset:5120
	ds_read_b64_tr_b16 v[234:235], v173 offset:7168
	s_waitcnt lgkmcnt(10)
	v_mfma_f32_32x32x16_bf16 v[0:15], v[176:179], v[194:197], v[0:15]
	ds_read_b64_tr_b16 v[236:237], v173 offset:5632
	ds_read_b64_tr_b16 v[238:239], v173 offset:7680
	v_exp_f32_e32 v64, v64
	v_exp_f32_e32 v65, v65
	s_waitcnt lgkmcnt(11)
	v_mfma_f32_32x32x16_bf16 v[80:95], v[202:205], v[96:99], v[80:95]
	ds_read_b64_tr_b16 v[240:241], v173 offset:8192
	ds_read_b64_tr_b16 v[242:243], v173 offset:10240
	v_add_f32_e32 v167, v167, v65
	v_add_f32_e32 v167, v167, v64
	v_exp_f32_e32 v66, v66
	v_exp_f32_e32 v67, v67
	s_waitcnt lgkmcnt(12)
	v_mfma_f32_32x32x16_bf16 v[80:95], v[206:209], v[100:103], v[80:95]
	ds_read_b64_tr_b16 v[244:245], v173 offset:8704
	ds_read_b64_tr_b16 v[246:247], v173 offset:10752
	v_add_f32_e32 v167, v167, v67
	v_add_f32_e32 v167, v167, v66
	v_exp_f32_e32 v68, v68
	v_exp_f32_e32 v69, v69
	s_waitcnt lgkmcnt(13)
	v_mfma_f32_32x32x16_bf16 v[80:95], v[210:213], v[104:107], v[80:95]
	ds_read_b64_tr_b16 v[248:249], v173 offset:9216
	ds_read_b64_tr_b16 v[250:251], v173 offset:11264
	v_add_f32_e32 v167, v167, v69
	v_add_f32_e32 v167, v167, v68
	v_exp_f32_e32 v70, v70
	v_exp_f32_e32 v71, v71
	s_waitcnt lgkmcnt(14)
	v_mfma_f32_32x32x16_bf16 v[80:95], v[214:217], v[108:111], v[80:95]
	ds_read_b64_tr_b16 v[194:195], v173 offset:9728
	ds_read_b64_tr_b16 v[196:197], v173 offset:11776
	v_cvt_pk_bf16_f32 v176, v64, v65
	v_add_f32_e32 v167, v167, v71
	v_add_f32_e32 v167, v167, v70
	v_exp_f32_e32 v72, v72
	v_exp_f32_e32 v73, v73
	s_waitcnt lgkmcnt(14)
	v_mfma_f32_32x32x16_bf16 v[48:63], v[180:183], v[218:221], v[48:63]
	ds_read_b64_tr_b16 v[202:203], v173 offset:12288
	ds_read_b64_tr_b16 v[204:205], v173 offset:14336
	v_cvt_pk_bf16_f32 v177, v66, v67
	v_add_f32_e32 v167, v167, v73
	v_add_f32_e32 v167, v167, v72
	v_exp_f32_e32 v74, v74
	v_exp_f32_e32 v75, v75
	s_waitcnt lgkmcnt(14)
	v_mfma_f32_32x32x16_bf16 v[32:47], v[180:183], v[222:225], v[32:47]
	ds_read_b64_tr_b16 v[206:207], v173 offset:12800
	ds_read_b64_tr_b16 v[208:209], v173 offset:14848
	v_cvt_pk_bf16_f32 v178, v68, v69
	v_add_f32_e32 v167, v167, v75
	v_add_f32_e32 v167, v167, v74
	v_exp_f32_e32 v76, v76
	v_exp_f32_e32 v77, v77
	s_waitcnt lgkmcnt(14)
	v_mfma_f32_32x32x16_bf16 v[16:31], v[180:183], v[232:235], v[16:31]
	ds_read_b64_tr_b16 v[210:211], v173 offset:13312
	ds_read_b64_tr_b16 v[212:213], v173 offset:15360
	v_cvt_pk_bf16_f32 v179, v70, v71
	v_add_f32_e32 v167, v167, v77
	v_add_f32_e32 v167, v167, v76
	v_exp_f32_e32 v78, v78
	v_exp_f32_e32 v79, v79
	v_exp_f32_e32 v80, v80
	v_exp_f32_e32 v81, v81
	v_exp_f32_e32 v82, v82
	s_waitcnt lgkmcnt(14)
	v_mfma_f32_32x32x16_bf16 v[0:15], v[180:183], v[236:239], v[0:15]
	ds_read_b64_tr_b16 v[214:215], v173 offset:13824
	ds_read_b64_tr_b16 v[216:217], v173 offset:15872
	v_add_f32_e32 v167, v167, v79
	v_add_f32_e32 v167, v167, v78
	v_exp_f32_e32 v83, v83
	v_exp_f32_e32 v84, v84
	v_exp_f32_e32 v85, v85
	s_waitcnt lgkmcnt(14)
	v_mfma_f32_32x32x16_bf16 v[48:63], v[186:189], v[240:243], v[48:63]
	v_cvt_pk_bf16_f32 v181, v74, v75
	v_cvt_pk_bf16_f32 v180, v72, v73
	v_exp_f32_e32 v86, v86
	v_exp_f32_e32 v87, v87
	v_exp_f32_e32 v88, v88
	s_waitcnt lgkmcnt(12)
	v_mfma_f32_32x32x16_bf16 v[32:47], v[186:189], v[244:247], v[32:47]
	v_cvt_pk_bf16_f32 v199, v82, v83
	v_cvt_pk_bf16_f32 v198, v80, v81
	v_cvt_pk_bf16_f32 v183, v78, v79
	v_cvt_pk_bf16_f32 v182, v76, v77
	v_exp_f32_e32 v89, v89
	v_exp_f32_e32 v90, v90
	v_exp_f32_e32 v91, v91
	s_waitcnt lgkmcnt(10)
	v_mfma_f32_32x32x16_bf16 v[16:31], v[186:189], v[248:251], v[16:31]
	v_cvt_pk_bf16_f32 v201, v86, v87
	v_cvt_pk_bf16_f32 v200, v84, v85
	v_exp_f32_e32 v92, v92
	v_exp_f32_e32 v93, v93
	s_waitcnt lgkmcnt(8)
	v_mfma_f32_32x32x16_bf16 v[0:15], v[186:189], v[194:197], v[0:15]
	v_exp_f32_e32 v94, v94
	v_exp_f32_e32 v95, v95
	v_cvt_pk_bf16_f32 v154, v88, v89
	v_cvt_pk_bf16_f32 v155, v90, v91
	v_cvt_pk_bf16_f32 v156, v92, v93
	v_cvt_pk_bf16_f32 v157, v94, v95
	s_waitcnt lgkmcnt(0)
	s_waitcnt vmcnt(0)
	s_barrier
; DEV void attn_a_item(const Params& P, int layer, int batch, int item, char* lds) {
;     ...
;   for (int j = jlo; j <= jhi; ++j) {
;     const int bcur = (j - jlo) & 1;
;     const char* Ks = K_lds + bcur * 16384;
;     f32x16 p0, p1;
;     {
;       const float dbase = (float)(j * 64 - qpos + 4 * hi);
;       const int q0 = qb * 128;
;       if (j * 64 + 63 < q0 || j * 64 > q0 + 127) {
;         const float step = (j * 64 < q0) ? -nslope : nslope;
;         const float base = fmaf(dbase, step, nMC), step8 = 8.f * step;
;         p0[0] = base; p0[1] = base + step; p0[2] = fmaf(2.f, step, base); p0[3] = fmaf(3.f, step, base);
; #pragma unroll
;         for (int r = 4; r < 16; ++r) p0[r] = p0[r - 4] + step8;
; #pragma unroll
;         for (int r = 0; r < 4; ++r) p1[r] = p0[r + 12] + step8;
; #pragma unroll
;         for (int r = 4; r < 16; ++r) p1[r] = p1[r - 4] + step8;
;       } else {
;         float d0[16], d1[16];
;         d0[0] = dbase; d0[1] = dbase + 1.f; d0[2] = dbase + 2.f; d0[3] = d0[1] + 2.f;
; #pragma unroll
;         for (int r = 4; r < 16; ++r) d0[r] = d0[r - 4] + 8.f;
; #pragma unroll
;         for (int r = 0; r < 4; ++r) d1[r] = d0[r + 12] + 8.f;
; #pragma unroll
;         for (int r = 4; r < 16; ++r) d1[r] = d1[r - 4] + 8.f;
; #pragma unroll
;         for (int r = 0; r < 16; ++r) { p0[r] = fmaf(fabsf(d0[r]), nslope, nMC); p1[r] = fmaf(fabsf(d1[r]), nslope, nMC); }
;       }
;     }
;     const int vb = vb0 + bcur * 16384;
;     bf16x8 pa0, pa1, pa2, pa3;
;     s16x4 fa[8], fb[8];
;     bf16x8 kf[8];
; #pragma unroll
;     for (int ks = 0; ks < 4; ++ks) {
;       const int cb = c * 128 + (ks * 16 + hi * 8) * 2;
;       kf[2 * ks] = *reinterpret_cast<const bf16x8*>(Ks + KSWZ(r32, cb));
;       kf[2 * ks + 1] = *reinterpret_cast<const bf16x8*>(Ks + KSWZ(32 + r32, cb));
;     }
; #pragma unroll
;     for (int ks = 0; ks < 4; ++ks) p0 = __builtin_amdgcn_mfma_f32_32x32x16_bf16(kf[2 * ks], qr[ks], p0, 0, 0, 0);
;     SBAR();
;     if (j + 1 <= jhi) ALOAD(bcur ^ 1, (j + 1) * 64);
;     SBAR();
;     trq<0, 0>(vb, fa);
; #pragma unroll
;     for (int ks = 0; ks < 4; ++ks) p1 = __builtin_amdgcn_mfma_f32_32x32x16_bf16(kf[2 * ks + 1], qr[ks], p1, 0, 0, 0);
;     sm_exp(p0, lsum); sm_pack(p0, pa0, pa1);
;     asm volatile("s_waitcnt lgkmcnt(0)" ::: "memory"); SBAR();
;     trq<0, 2>(vb, fb);
;     mmaq(o[0], o[1], fa, pa0, pa1);
;     sm_exp(p1, lsum);
	s_cmp_ge_i32 s2, s70
	s_cbranch_scc1 .Ldfa_drain1
	s_add_u32 s2, s2, 1
	s_add_u32 s24, s24, 64
	s_cmp_lt_i32 s2, s78
	s_cselect_b32 s3, s65, s25
	s_sub_u32 s71, s2, s78
	s_cmp_lt_u32 s71, 2
	s_cselect_b64 vcc, -1, 0
	v_cvt_f32_i32_e32 v129, s24
	s_nop 0
	v_fma_f32 v168, v129, s3, v132
	ds_read_b128 v[218:221], v169 offset:0
	ds_read_b128 v[222:225], v170 offset:0
	ds_read_b128 v[232:235], v171 offset:0
	ds_read_b128 v[236:239], v172 offset:0
	v_mfma_f32_32x32x16_bf16 v[48:63], v[150:153], v[202:205], v[48:63]
	ds_read_b64_tr_b16 v[240:241], v173 offset:16384
	ds_read_b64_tr_b16 v[242:243], v173 offset:18432
	s_cbranch_vccnz .Ldfa_diag_e_a
	v_fma_f32 v64, v112, s3, v168
	v_fma_f32 v65, v113, s3, v168
	v_fma_f32 v66, v114, s3, v168
	v_fma_f32 v67, v115, s3, v168
	v_fma_f32 v68, v116, s3, v168
	v_fma_f32 v69, v117, s3, v168
	v_fma_f32 v70, v118, s3, v168
	v_fma_f32 v71, v119, s3, v168
.Ldfa_back_e_a:
	v_mfma_f32_32x32x16_bf16 v[32:47], v[150:153], v[206:209], v[32:47]
	ds_read_b64_tr_b16 v[244:245], v173 offset:16896
	ds_read_b64_tr_b16 v[246:247], v173 offset:18944
	v_mfma_f32_32x32x16_bf16 v[16:31], v[150:153], v[210:213], v[16:31]
	ds_read_b64_tr_b16 v[248:249], v173 offset:17408
	ds_read_b64_tr_b16 v[250:251], v173 offset:19456
	s_cbranch_vccnz .Ldfa_diag_e_b
	v_fma_f32 v72, v120, s3, v168
	v_fma_f32 v73, v121, s3, v168
	v_fma_f32 v74, v122, s3, v168
	v_fma_f32 v75, v123, s3, v168
	v_fma_f32 v76, v124, s3, v168
	v_fma_f32 v77, v125, s3, v168
	v_fma_f32 v78, v126, s3, v168
	v_fma_f32 v79, v127, s3, v168
.Ldfa_back_e_b:
	v_mfma_f32_32x32x16_bf16 v[0:15], v[150:153], v[214:217], v[0:15]
	ds_read_b64_tr_b16 v[194:195], v173 offset:17920
	ds_read_b64_tr_b16 v[196:197], v173 offset:19968
	s_waitcnt lgkmcnt(11)
	v_mfma_f32_32x32x16_bf16 v[64:79], v[218:221], v[96:99], v[64:79]
	ds_read_b128 v[202:205], v169 offset:8192
	v_add_f32_e32 v167, v167, v80
	v_add_f32_e32 v167, v167, v81
	v_add_f32_e32 v167, v167, v82
	v_add_f32_e32 v167, v167, v83
	s_waitcnt lgkmcnt(11)
	v_mfma_f32_32x32x16_bf16 v[64:79], v[222:225], v[100:103], v[64:79]
	ds_read_b128 v[206:209], v170 offset:8192
	v_add_f32_e32 v167, v167, v84
	v_add_f32_e32 v167, v167, v85
	v_add_f32_e32 v167, v167, v86
	v_add_f32_e32 v167, v167, v87
	s_add_u32 m0, s100, 0x0
	s_nop 0
	global_load_lds_dwordx4 v149, s[74:75]
	s_add_u32 m0, s100, 0x2000
	s_nop 0
	global_load_lds_dwordx4 v131, s[74:75]
	s_add_u32 s74, s74, 0x10000
	s_addc_u32 s75, s75, 0
	s_cmp_ge_i32 s2, s70
	s_cbranch_scc1 .Ldfa_skipk_e
	s_add_u32 m0, s100, 0xc000
	s_nop 0
	global_load_lds_dwordx4 v174, s[68:69]
	s_add_u32 m0, s100, 0xe000
	s_nop 0
	global_load_lds_dwordx4 v175, s[68:69]
	s_add_u32 s68, s68, 0x10000
	s_addc_u32 s69, s69, 0
.Ldfa_skipk_e:
	s_waitcnt lgkmcnt(11)
	v_mfma_f32_32x32x16_bf16 v[64:79], v[232:235], v[104:107], v[64:79]
	ds_read_b128 v[210:213], v171 offset:8192
	v_add_f32_e32 v167, v167, v88
	v_add_f32_e32 v167, v167, v89
	v_add_f32_e32 v167, v167, v90
	v_add_f32_e32 v167, v167, v91
	s_waitcnt lgkmcnt(11)
	v_mfma_f32_32x32x16_bf16 v[64:79], v[236:239], v[108:111], v[64:79]
	ds_read_b128 v[214:217], v172 offset:8192
	v_add_f32_e32 v167, v167, v92
	v_add_f32_e32 v167, v167, v93
	v_add_f32_e32 v167, v167, v94
	v_add_f32_e32 v167, v167, v95
	s_waitcnt lgkmcnt(10)
	v_mfma_f32_32x32x16_bf16 v[48:63], v[176:179], v[240:243], v[48:63]
	ds_read_b64_tr_b16 v[218:219], v173 offset:20480
	ds_read_b64_tr_b16 v[220:221], v173 offset:22528
	s_cbranch_vccnz .Ldfa_diag_e_c
	v_fma_f32 v80, v133, s3, v168
	v_fma_f32 v81, v134, s3, v168
	v_fma_f32 v82, v135, s3, v168
	v_fma_f32 v83, v136, s3, v168
	v_fma_f32 v84, v137, s3, v168
	v_fma_f32 v85, v138, s3, v168
	v_fma_f32 v86, v139, s3, v168
	v_fma_f32 v87, v140, s3, v168
.Ldfa_back_e_c:
	s_waitcnt lgkmcnt(10)
	v_mfma_f32_32x32x16_bf16 v[32:47], v[176:179], v[244:247], v[32:47]
	ds_read_b64_tr_b16 v[222:223], v173 offset:20992
	ds_read_b64_tr_b16 v[224:225], v173 offset:23040
	s_cbranch_vccnz .Ldfa_diag_e_d
	v_fma_f32 v88, v141, s3, v168
	v_fma_f32 v89, v142, s3, v168
	v_fma_f32 v90, v143, s3, v168
	v_fma_f32 v91, v144, s3, v168
	v_fma_f32 v92, v145, s3, v168
	v_fma_f32 v93, v146, s3, v168
	v_fma_f32 v94, v147, s3, v168
	v_fma_f32 v95, v148, s3, v168
.Ldfa_back_e_d:
	s_waitcnt lgkmcnt(10)
	v_mfma_f32_32x32x16_bf16 v[16:31], v[176:179], v[248:251], v[16:31]
	ds_read_b64_tr_b16 v[232:233], v173 offset:21504
	ds_read_b64_tr_b16 v[234:235], v173 offset:23552
	s_waitcnt lgkmcnt(10)
	v_mfma_f32_32x32x16_bf16 v[0:15], v[176:179], v[194:197], v[0:15]
	ds_read_b64_tr_b16 v[236:237], v173 offset:22016
	ds_read_b64_tr_b16 v[238:239], v173 offset:24064
	v_exp_f32_e32 v64, v64
	v_exp_f32_e32 v65, v65
	s_waitcnt lgkmcnt(11)
	v_mfma_f32_32x32x16_bf16 v[80:95], v[202:205], v[96:99], v[80:95]
	ds_read_b64_tr_b16 v[240:241], v173 offset:24576
	ds_read_b64_tr_b16 v[242:243], v173 offset:26624
	v_add_f32_e32 v167, v167, v65
	v_add_f32_e32 v167, v167, v64
	v_exp_f32_e32 v66, v66
	v_exp_f32_e32 v67, v67
	s_waitcnt lgkmcnt(12)
	v_mfma_f32_32x32x16_bf16 v[80:95], v[206:209], v[100:103], v[80:95]
	ds_read_b64_tr_b16 v[244:245], v173 offset:25088
	ds_read_b64_tr_b16 v[246:247], v173 offset:27136
	v_add_f32_e32 v167, v167, v67
	v_add_f32_e32 v167, v167, v66
	v_exp_f32_e32 v68, v68
	v_exp_f32_e32 v69, v69
	s_waitcnt lgkmcnt(13)
	v_mfma_f32_32x32x16_bf16 v[80:95], v[210:213], v[104:107], v[80:95]
	ds_read_b64_tr_b16 v[248:249], v173 offset:25600
	ds_read_b64_tr_b16 v[250:251], v173 offset:27648
	v_add_f32_e32 v167, v167, v69
	v_add_f32_e32 v167, v167, v68
	v_exp_f32_e32 v70, v70
	v_exp_f32_e32 v71, v71
	s_waitcnt lgkmcnt(14)
; #define SBAR() __builtin_amdgcn_sched_barrier(0)
; DEV void attn_a_item(const Params& P, int layer, int batch, int item, char* lds) {
;     ...
;     trq<0, 0>(vb, fa);
; #pragma unroll
;     for (int ks = 0; ks < 4; ++ks) p1 = __builtin_amdgcn_mfma_f32_32x32x16_bf16(kf[2 * ks + 1], qr[ks], p1, 0, 0, 0);
;     sm_exp(p0, lsum); sm_pack(p0, pa0, pa1);
;     asm volatile("s_waitcnt lgkmcnt(0)" ::: "memory"); SBAR();
;     trq<0, 2>(vb, fb);
;     mmaq(o[0], o[1], fa, pa0, pa1);
;     sm_exp(p1, lsum);
;     asm volatile("s_waitcnt lgkmcnt(0)" ::: "memory"); SBAR();
;     trq<2, 0>(vb, fa);
;     mmaq(o[2], o[3], fb, pa0, pa1);
;     sm_pack(p1, pa2, pa3);
;     asm volatile("s_waitcnt lgkmcnt(0)" ::: "memory"); SBAR();
;     trq<2, 2>(vb, fb);
;     mmaq(o[0], o[1], fa, pa2, pa3);
;     asm volatile("s_waitcnt lgkmcnt(0)" ::: "memory"); SBAR();
;     mmaq(o[2], o[3], fb, pa2, pa3);
;     asm volatile("s_waitcnt vmcnt(0)" ::: "memory");
;     __syncthreads();
;   }
	v_mfma_f32_32x32x16_bf16 v[80:95], v[214:217], v[108:111], v[80:95]
	ds_read_b64_tr_b16 v[194:195], v173 offset:26112
	ds_read_b64_tr_b16 v[196:197], v173 offset:28160
	v_cvt_pk_bf16_f32 v176, v64, v65
	v_add_f32_e32 v167, v167, v71
	v_add_f32_e32 v167, v167, v70
	v_exp_f32_e32 v72, v72
	v_exp_f32_e32 v73, v73
	s_waitcnt lgkmcnt(14)
	v_mfma_f32_32x32x16_bf16 v[48:63], v[180:183], v[218:221], v[48:63]
	ds_read_b64_tr_b16 v[202:203], v173 offset:28672
	ds_read_b64_tr_b16 v[204:205], v173 offset:30720
	v_cvt_pk_bf16_f32 v177, v66, v67
	v_add_f32_e32 v167, v167, v73
	v_add_f32_e32 v167, v167, v72
	v_exp_f32_e32 v74, v74
	v_exp_f32_e32 v75, v75
	s_waitcnt lgkmcnt(14)
	v_mfma_f32_32x32x16_bf16 v[32:47], v[180:183], v[222:225], v[32:47]
	ds_read_b64_tr_b16 v[206:207], v173 offset:29184
	ds_read_b64_tr_b16 v[208:209], v173 offset:31232
	v_cvt_pk_bf16_f32 v178, v68, v69
	v_add_f32_e32 v167, v167, v75
	v_add_f32_e32 v167, v167, v74
	v_exp_f32_e32 v76, v76
	v_exp_f32_e32 v77, v77
	s_waitcnt lgkmcnt(14)
	v_mfma_f32_32x32x16_bf16 v[16:31], v[180:183], v[232:235], v[16:31]
	ds_read_b64_tr_b16 v[210:211], v173 offset:29696
	ds_read_b64_tr_b16 v[212:213], v173 offset:31744
	v_cvt_pk_bf16_f32 v179, v70, v71
	v_add_f32_e32 v167, v167, v77
	v_add_f32_e32 v167, v167, v76
	v_exp_f32_e32 v78, v78
	v_exp_f32_e32 v79, v79
	v_exp_f32_e32 v80, v80
	v_exp_f32_e32 v81, v81
	v_exp_f32_e32 v82, v82
	s_waitcnt lgkmcnt(14)
	v_mfma_f32_32x32x16_bf16 v[0:15], v[180:183], v[236:239], v[0:15]
	ds_read_b64_tr_b16 v[214:215], v173 offset:30208
	ds_read_b64_tr_b16 v[216:217], v173 offset:32256
	v_add_f32_e32 v167, v167, v79
	v_add_f32_e32 v167, v167, v78
	v_exp_f32_e32 v83, v83
	v_exp_f32_e32 v84, v84
	v_exp_f32_e32 v85, v85
	s_waitcnt lgkmcnt(14)
	v_mfma_f32_32x32x16_bf16 v[48:63], v[198:201], v[240:243], v[48:63]
	v_cvt_pk_bf16_f32 v181, v74, v75
	v_cvt_pk_bf16_f32 v180, v72, v73
	v_exp_f32_e32 v86, v86
	v_exp_f32_e32 v87, v87
	v_exp_f32_e32 v88, v88
	s_waitcnt lgkmcnt(12)
	v_mfma_f32_32x32x16_bf16 v[32:47], v[198:201], v[244:247], v[32:47]
	v_cvt_pk_bf16_f32 v187, v82, v83
	v_cvt_pk_bf16_f32 v186, v80, v81
	v_cvt_pk_bf16_f32 v183, v78, v79
	v_cvt_pk_bf16_f32 v182, v76, v77
	v_exp_f32_e32 v89, v89
	v_exp_f32_e32 v90, v90
	v_exp_f32_e32 v91, v91
	s_waitcnt lgkmcnt(10)
	v_mfma_f32_32x32x16_bf16 v[16:31], v[198:201], v[248:251], v[16:31]
	v_cvt_pk_bf16_f32 v189, v86, v87
	v_cvt_pk_bf16_f32 v188, v84, v85
	v_exp_f32_e32 v92, v92
	v_exp_f32_e32 v93, v93
	s_waitcnt lgkmcnt(8)
	v_mfma_f32_32x32x16_bf16 v[0:15], v[198:201], v[194:197], v[0:15]
	v_exp_f32_e32 v94, v94
	v_exp_f32_e32 v95, v95
	v_cvt_pk_bf16_f32 v150, v88, v89
	v_cvt_pk_bf16_f32 v151, v90, v91
	v_cvt_pk_bf16_f32 v152, v92, v93
	v_cvt_pk_bf16_f32 v153, v94, v95
	s_waitcnt lgkmcnt(0)
	s_waitcnt vmcnt(0)
	s_barrier
	s_cmp_ge_i32 s2, s70
	s_cbranch_scc1 .Ldfa_drain0
	s_add_u32 s2, s2, 1
	s_add_u32 s24, s24, 64
	s_branch .Ldfa_loop
.Ldfa_drain1:
	ds_read_b64_tr_b16 v[218:219], v173 offset:16384
	ds_read_b64_tr_b16 v[220:221], v173 offset:18432
	ds_read_b64_tr_b16 v[222:223], v173 offset:16896
	ds_read_b64_tr_b16 v[224:225], v173 offset:18944
	ds_read_b64_tr_b16 v[232:233], v173 offset:17408
	ds_read_b64_tr_b16 v[234:235], v173 offset:19456
	ds_read_b64_tr_b16 v[236:237], v173 offset:17920
	ds_read_b64_tr_b16 v[238:239], v173 offset:19968
	ds_read_b64_tr_b16 v[240:241], v173 offset:20480
	ds_read_b64_tr_b16 v[242:243], v173 offset:22528
	ds_read_b64_tr_b16 v[244:245], v173 offset:20992
	ds_read_b64_tr_b16 v[246:247], v173 offset:23040
	ds_read_b64_tr_b16 v[248:249], v173 offset:21504
	ds_read_b64_tr_b16 v[250:251], v173 offset:23552
	ds_read_b64_tr_b16 v[194:195], v173 offset:22016
	ds_read_b64_tr_b16 v[196:197], v173 offset:24064
	v_mfma_f32_32x32x16_bf16 v[48:63], v[150:153], v[202:205], v[48:63]
	ds_read_b64_tr_b16 v[202:203], v173 offset:24576
	ds_read_b64_tr_b16 v[204:205], v173 offset:26624
	v_mfma_f32_32x32x16_bf16 v[32:47], v[150:153], v[206:209], v[32:47]
	ds_read_b64_tr_b16 v[206:207], v173 offset:25088
	ds_read_b64_tr_b16 v[208:209], v173 offset:27136
	v_mfma_f32_32x32x16_bf16 v[16:31], v[150:153], v[210:213], v[16:31]
	ds_read_b64_tr_b16 v[210:211], v173 offset:25600
	ds_read_b64_tr_b16 v[212:213], v173 offset:27648
	v_mfma_f32_32x32x16_bf16 v[0:15], v[150:153], v[214:217], v[0:15]
	ds_read_b64_tr_b16 v[214:215], v173 offset:26112
	ds_read_b64_tr_b16 v[216:217], v173 offset:28160
	v_mfma_f32_32x32x16_bf16 v[48:63], v[176:179], v[218:221], v[48:63]
	ds_read_b64_tr_b16 v[218:219], v173 offset:28672
	ds_read_b64_tr_b16 v[220:221], v173 offset:30720
	v_mfma_f32_32x32x16_bf16 v[32:47], v[176:179], v[222:225], v[32:47]
	ds_read_b64_tr_b16 v[222:223], v173 offset:29184
	ds_read_b64_tr_b16 v[224:225], v173 offset:31232
	v_mfma_f32_32x32x16_bf16 v[16:31], v[176:179], v[232:235], v[16:31]
	ds_read_b64_tr_b16 v[232:233], v173 offset:29696
	ds_read_b64_tr_b16 v[234:235], v173 offset:31744
	v_mfma_f32_32x32x16_bf16 v[0:15], v[176:179], v[236:239], v[0:15]
	ds_read_b64_tr_b16 v[236:237], v173 offset:30208
	ds_read_b64_tr_b16 v[238:239], v173 offset:32256
	v_mfma_f32_32x32x16_bf16 v[48:63], v[180:183], v[240:243], v[48:63]
	v_mfma_f32_32x32x16_bf16 v[32:47], v[180:183], v[244:247], v[32:47]
	v_mfma_f32_32x32x16_bf16 v[16:31], v[180:183], v[248:251], v[16:31]
	v_mfma_f32_32x32x16_bf16 v[0:15], v[180:183], v[194:197], v[0:15]
	s_waitcnt lgkmcnt(14)
	v_mfma_f32_32x32x16_bf16 v[48:63], v[198:201], v[202:205], v[48:63]
	s_waitcnt lgkmcnt(12)
	v_mfma_f32_32x32x16_bf16 v[32:47], v[198:201], v[206:209], v[32:47]
	s_waitcnt lgkmcnt(10)
	v_mfma_f32_32x32x16_bf16 v[16:31], v[198:201], v[210:213], v[16:31]
	s_waitcnt lgkmcnt(8)
	v_mfma_f32_32x32x16_bf16 v[0:15], v[198:201], v[214:217], v[0:15]
	s_waitcnt lgkmcnt(6)
	v_mfma_f32_32x32x16_bf16 v[48:63], v[154:157], v[218:221], v[48:63]
	s_waitcnt lgkmcnt(4)
	v_mfma_f32_32x32x16_bf16 v[32:47], v[154:157], v[222:225], v[32:47]
	s_waitcnt lgkmcnt(2)
	v_mfma_f32_32x32x16_bf16 v[16:31], v[154:157], v[232:235], v[16:31]
	s_waitcnt lgkmcnt(0)
	v_mfma_f32_32x32x16_bf16 v[0:15], v[154:157], v[236:239], v[0:15]
	v_add_f32_e32 v167, v167, v80
	v_add_f32_e32 v167, v167, v81
	v_add_f32_e32 v167, v167, v82
	v_add_f32_e32 v167, v167, v83
	v_add_f32_e32 v167, v167, v84
	v_add_f32_e32 v167, v167, v85
	v_add_f32_e32 v167, v167, v86
	v_add_f32_e32 v167, v167, v87
	v_add_f32_e32 v167, v167, v88
	v_add_f32_e32 v167, v167, v89
	v_add_f32_e32 v167, v167, v90
	v_add_f32_e32 v167, v167, v91
	v_add_f32_e32 v167, v167, v92
	v_add_f32_e32 v167, v167, v93
	v_add_f32_e32 v167, v167, v94
	v_add_f32_e32 v167, v167, v95
	s_branch .LBB0_383
; #define SBAR() __builtin_amdgcn_sched_barrier(0)
; DEV void attn_a_item(const Params& P, int layer, int batch, int item, char* lds) {
;     ...
;     trq<0, 0>(vb, fa);
; #pragma unroll
;     for (int ks = 0; ks < 4; ++ks) p1 = __builtin_amdgcn_mfma_f32_32x32x16_bf16(kf[2 * ks + 1], qr[ks], p1, 0, 0, 0);
;     sm_exp(p0, lsum); sm_pack(p0, pa0, pa1);
;     asm volatile("s_waitcnt lgkmcnt(0)" ::: "memory"); SBAR();
;     trq<0, 2>(vb, fb);
;     mmaq(o[0], o[1], fa, pa0, pa1);
;     sm_exp(p1, lsum);
;     asm volatile("s_waitcnt lgkmcnt(0)" ::: "memory"); SBAR();
;     trq<2, 0>(vb, fa);
;     mmaq(o[2], o[3], fb, pa0, pa1);
;     sm_pack(p1, pa2, pa3);
;     asm volatile("s_waitcnt lgkmcnt(0)" ::: "memory"); SBAR();
;     trq<2, 2>(vb, fb);
;     mmaq(o[0], o[1], fa, pa2, pa3);
;     asm volatile("s_waitcnt lgkmcnt(0)" ::: "memory"); SBAR();
;     mmaq(o[2], o[3], fb, pa2, pa3);
;     asm volatile("s_waitcnt vmcnt(0)" ::: "memory");
;     __syncthreads();
.Ldfa_drain0_pre:
.Ldfa_drain0:
	ds_read_b64_tr_b16 v[218:219], v173 offset:0
	ds_read_b64_tr_b16 v[220:221], v173 offset:2048
	ds_read_b64_tr_b16 v[222:223], v173 offset:512
	ds_read_b64_tr_b16 v[224:225], v173 offset:2560
	ds_read_b64_tr_b16 v[232:233], v173 offset:1024
	ds_read_b64_tr_b16 v[234:235], v173 offset:3072
	ds_read_b64_tr_b16 v[236:237], v173 offset:1536
	ds_read_b64_tr_b16 v[238:239], v173 offset:3584
	ds_read_b64_tr_b16 v[240:241], v173 offset:4096
	ds_read_b64_tr_b16 v[242:243], v173 offset:6144
	ds_read_b64_tr_b16 v[244:245], v173 offset:4608
	ds_read_b64_tr_b16 v[246:247], v173 offset:6656
	ds_read_b64_tr_b16 v[248:249], v173 offset:5120
	ds_read_b64_tr_b16 v[250:251], v173 offset:7168
	ds_read_b64_tr_b16 v[194:195], v173 offset:5632
	ds_read_b64_tr_b16 v[196:197], v173 offset:7680
	v_mfma_f32_32x32x16_bf16 v[48:63], v[154:157], v[202:205], v[48:63]
	ds_read_b64_tr_b16 v[202:203], v173 offset:8192
	ds_read_b64_tr_b16 v[204:205], v173 offset:10240
	v_mfma_f32_32x32x16_bf16 v[32:47], v[154:157], v[206:209], v[32:47]
	ds_read_b64_tr_b16 v[206:207], v173 offset:8704
	ds_read_b64_tr_b16 v[208:209], v173 offset:10752
	v_mfma_f32_32x32x16_bf16 v[16:31], v[154:157], v[210:213], v[16:31]
	ds_read_b64_tr_b16 v[210:211], v173 offset:9216
	ds_read_b64_tr_b16 v[212:213], v173 offset:11264
	v_mfma_f32_32x32x16_bf16 v[0:15], v[154:157], v[214:217], v[0:15]
	ds_read_b64_tr_b16 v[214:215], v173 offset:9728
	ds_read_b64_tr_b16 v[216:217], v173 offset:11776
	v_mfma_f32_32x32x16_bf16 v[48:63], v[176:179], v[218:221], v[48:63]
	ds_read_b64_tr_b16 v[218:219], v173 offset:12288
	ds_read_b64_tr_b16 v[220:221], v173 offset:14336
	v_mfma_f32_32x32x16_bf16 v[32:47], v[176:179], v[222:225], v[32:47]
	ds_read_b64_tr_b16 v[222:223], v173 offset:12800
	ds_read_b64_tr_b16 v[224:225], v173 offset:14848
	v_mfma_f32_32x32x16_bf16 v[16:31], v[176:179], v[232:235], v[16:31]
	ds_read_b64_tr_b16 v[232:233], v173 offset:13312
	ds_read_b64_tr_b16 v[234:235], v173 offset:15360
	v_mfma_f32_32x32x16_bf16 v[0:15], v[176:179], v[236:239], v[0:15]
	ds_read_b64_tr_b16 v[236:237], v173 offset:13824
	ds_read_b64_tr_b16 v[238:239], v173 offset:15872
	v_mfma_f32_32x32x16_bf16 v[48:63], v[180:183], v[240:243], v[48:63]
	v_mfma_f32_32x32x16_bf16 v[32:47], v[180:183], v[244:247], v[32:47]
	v_mfma_f32_32x32x16_bf16 v[16:31], v[180:183], v[248:251], v[16:31]
	v_mfma_f32_32x32x16_bf16 v[0:15], v[180:183], v[194:197], v[0:15]
	s_waitcnt lgkmcnt(14)
	v_mfma_f32_32x32x16_bf16 v[48:63], v[186:189], v[202:205], v[48:63]
	s_waitcnt lgkmcnt(12)
	v_mfma_f32_32x32x16_bf16 v[32:47], v[186:189], v[206:209], v[32:47]
	s_waitcnt lgkmcnt(10)
	v_mfma_f32_32x32x16_bf16 v[16:31], v[186:189], v[210:213], v[16:31]
	s_waitcnt lgkmcnt(8)
	v_mfma_f32_32x32x16_bf16 v[0:15], v[186:189], v[214:217], v[0:15]
	s_waitcnt lgkmcnt(6)
	v_mfma_f32_32x32x16_bf16 v[48:63], v[150:153], v[218:221], v[48:63]
	s_waitcnt lgkmcnt(4)
	v_mfma_f32_32x32x16_bf16 v[32:47], v[150:153], v[222:225], v[32:47]
	s_waitcnt lgkmcnt(2)
	v_mfma_f32_32x32x16_bf16 v[16:31], v[150:153], v[232:235], v[16:31]
	s_waitcnt lgkmcnt(0)
	v_mfma_f32_32x32x16_bf16 v[0:15], v[150:153], v[236:239], v[0:15]
	v_add_f32_e32 v167, v167, v80
	v_add_f32_e32 v167, v167, v81
	v_add_f32_e32 v167, v167, v82
	v_add_f32_e32 v167, v167, v83
	v_add_f32_e32 v167, v167, v84
	v_add_f32_e32 v167, v167, v85
	v_add_f32_e32 v167, v167, v86
	v_add_f32_e32 v167, v167, v87
	v_add_f32_e32 v167, v167, v88
	v_add_f32_e32 v167, v167, v89
	v_add_f32_e32 v167, v167, v90
	v_add_f32_e32 v167, v167, v91
	v_add_f32_e32 v167, v167, v92
	v_add_f32_e32 v167, v167, v93
	v_add_f32_e32 v167, v167, v94
	v_add_f32_e32 v167, v167, v95
	s_branch .LBB0_383
; DEV void attn_a_item(const Params& P, int layer, int batch, int item, char* lds) {
;     ...
;       const float dbase = (float)(j * 64 - qpos + 4 * hi);
;       const int q0 = qb * 128;
;       if (j * 64 + 63 < q0 || j * 64 > q0 + 127) {
;         const float step = (j * 64 < q0) ? -nslope : nslope;
;         const float base = fmaf(dbase, step, nMC), step8 = 8.f * step;
;         p0[0] = base; p0[1] = base + step; p0[2] = fmaf(2.f, step, base); p0[3] = fmaf(3.f, step, base);
; #pragma unroll
;         for (int r = 4; r < 16; ++r) p0[r] = p0[r - 4] + step8;
; #pragma unroll
;         for (int r = 0; r < 4; ++r) p1[r] = p0[r + 12] + step8;
; #pragma unroll
;         for (int r = 4; r < 16; ++r) p1[r] = p1[r - 4] + step8;
;       } else {
;         float d0[16], d1[16];
;         d0[0] = dbase; d0[1] = dbase + 1.f; d0[2] = dbase + 2.f; d0[3] = d0[1] + 2.f;
; #pragma unroll
;         for (int r = 4; r < 16; ++r) d0[r] = d0[r - 4] + 8.f;
; #pragma unroll
;         for (int r = 0; r < 4; ++r) d1[r] = d0[r + 12] + 8.f;
; #pragma unroll
;         for (int r = 4; r < 16; ++r) d1[r] = d1[r - 4] + 8.f;
; #pragma unroll
;         for (int r = 0; r < 16; ++r) { p0[r] = fmaf(fabsf(d0[r]), nslope, nMC); p1[r] = fmaf(fabsf(d1[r]), nslope, nMC); }
;       }
.Ldfa_diag_f_a:
	v_add_f32_e32 v166, v129, v112
	v_fma_f32 v64, |v166|, v130, v132
	v_add_f32_e32 v166, v129, v113
	v_fma_f32 v65, |v166|, v130, v132
	v_add_f32_e32 v166, v129, v114
	v_fma_f32 v66, |v166|, v130, v132
	v_add_f32_e32 v166, v129, v115
	v_fma_f32 v67, |v166|, v130, v132
	v_add_f32_e32 v166, v129, v116
	v_fma_f32 v68, |v166|, v130, v132
	v_add_f32_e32 v166, v129, v117
	v_fma_f32 v69, |v166|, v130, v132
	v_add_f32_e32 v166, v129, v118
	v_fma_f32 v70, |v166|, v130, v132
	v_add_f32_e32 v166, v129, v119
	v_fma_f32 v71, |v166|, v130, v132
	v_add_f32_e32 v166, v129, v120
	v_fma_f32 v72, |v166|, v130, v132
	v_add_f32_e32 v166, v129, v121
	v_fma_f32 v73, |v166|, v130, v132
	v_add_f32_e32 v166, v129, v122
	v_fma_f32 v74, |v166|, v130, v132
	v_add_f32_e32 v166, v129, v123
	v_fma_f32 v75, |v166|, v130, v132
	v_add_f32_e32 v166, v129, v124
	v_fma_f32 v76, |v166|, v130, v132
	v_add_f32_e32 v166, v129, v125
	v_fma_f32 v77, |v166|, v130, v132
	v_add_f32_e32 v166, v129, v126
	v_fma_f32 v78, |v166|, v130, v132
	v_add_f32_e32 v166, v129, v127
	v_fma_f32 v79, |v166|, v130, v132
	s_branch .Ldfa_back_f_a
.Ldfa_diag_f_b:
	v_add_f32_e32 v166, v129, v133
	v_fma_f32 v80, |v166|, v130, v132
	v_add_f32_e32 v166, v129, v134
	v_fma_f32 v81, |v166|, v130, v132
	v_add_f32_e32 v166, v129, v135
	v_fma_f32 v82, |v166|, v130, v132
	v_add_f32_e32 v166, v129, v136
	v_fma_f32 v83, |v166|, v130, v132
	v_add_f32_e32 v166, v129, v137
	v_fma_f32 v84, |v166|, v130, v132
	v_add_f32_e32 v166, v129, v138
	v_fma_f32 v85, |v166|, v130, v132
	v_add_f32_e32 v166, v129, v139
	v_fma_f32 v86, |v166|, v130, v132
	v_add_f32_e32 v166, v129, v140
	v_fma_f32 v87, |v166|, v130, v132
	v_add_f32_e32 v166, v129, v141
	v_fma_f32 v88, |v166|, v130, v132
	v_add_f32_e32 v166, v129, v142
	v_fma_f32 v89, |v166|, v130, v132
	v_add_f32_e32 v166, v129, v143
	v_fma_f32 v90, |v166|, v130, v132
	v_add_f32_e32 v166, v129, v144
	v_fma_f32 v91, |v166|, v130, v132
	v_add_f32_e32 v166, v129, v145
	v_fma_f32 v92, |v166|, v130, v132
	v_add_f32_e32 v166, v129, v146
	v_fma_f32 v93, |v166|, v130, v132
	v_add_f32_e32 v166, v129, v147
	v_fma_f32 v94, |v166|, v130, v132
	v_add_f32_e32 v166, v129, v148
	v_fma_f32 v95, |v166|, v130, v132
	s_branch .Ldfa_back_f_b
.Ldfa_diag_o_a:
	v_add_f32_e32 v166, v129, v112
	v_fma_f32 v64, |v166|, v130, v132
	v_add_f32_e32 v166, v129, v113
	v_fma_f32 v65, |v166|, v130, v132
	v_add_f32_e32 v166, v129, v114
	v_fma_f32 v66, |v166|, v130, v132
	v_add_f32_e32 v166, v129, v115
	v_fma_f32 v67, |v166|, v130, v132
	v_add_f32_e32 v166, v129, v116
	v_fma_f32 v68, |v166|, v130, v132
	v_add_f32_e32 v166, v129, v117
	v_fma_f32 v69, |v166|, v130, v132
	v_add_f32_e32 v166, v129, v118
	v_fma_f32 v70, |v166|, v130, v132
	v_add_f32_e32 v166, v129, v119
	v_fma_f32 v71, |v166|, v130, v132
	s_branch .Ldfa_back_o_a
.Ldfa_diag_o_b:
	v_add_f32_e32 v166, v129, v120
	v_fma_f32 v72, |v166|, v130, v132
	v_add_f32_e32 v166, v129, v121
	v_fma_f32 v73, |v166|, v130, v132
	v_add_f32_e32 v166, v129, v122
	v_fma_f32 v74, |v166|, v130, v132
	v_add_f32_e32 v166, v129, v123
	v_fma_f32 v75, |v166|, v130, v132
	v_add_f32_e32 v166, v129, v124
	v_fma_f32 v76, |v166|, v130, v132
	v_add_f32_e32 v166, v129, v125
	v_fma_f32 v77, |v166|, v130, v132
	v_add_f32_e32 v166, v129, v126
	v_fma_f32 v78, |v166|, v130, v132
	v_add_f32_e32 v166, v129, v127
	v_fma_f32 v79, |v166|, v130, v132
	s_branch .Ldfa_back_o_b
.Ldfa_diag_o_c:
	v_add_f32_e32 v166, v129, v133
	v_fma_f32 v80, |v166|, v130, v132
	v_add_f32_e32 v166, v129, v134
	v_fma_f32 v81, |v166|, v130, v132
	v_add_f32_e32 v166, v129, v135
	v_fma_f32 v82, |v166|, v130, v132
	v_add_f32_e32 v166, v129, v136
	v_fma_f32 v83, |v166|, v130, v132
	v_add_f32_e32 v166, v129, v137
	v_fma_f32 v84, |v166|, v130, v132
	v_add_f32_e32 v166, v129, v138
	v_fma_f32 v85, |v166|, v130, v132
	v_add_f32_e32 v166, v129, v139
	v_fma_f32 v86, |v166|, v130, v132
	v_add_f32_e32 v166, v129, v140
	v_fma_f32 v87, |v166|, v130, v132
	s_branch .Ldfa_back_o_c
.Ldfa_diag_o_d:
	v_add_f32_e32 v166, v129, v141
	v_fma_f32 v88, |v166|, v130, v132
	v_add_f32_e32 v166, v129, v142
	v_fma_f32 v89, |v166|, v130, v132
	v_add_f32_e32 v166, v129, v143
	v_fma_f32 v90, |v166|, v130, v132
	v_add_f32_e32 v166, v129, v144
	v_fma_f32 v91, |v166|, v130, v132
	v_add_f32_e32 v166, v129, v145
	v_fma_f32 v92, |v166|, v130, v132
	v_add_f32_e32 v166, v129, v146
	v_fma_f32 v93, |v166|, v130, v132
	v_add_f32_e32 v166, v129, v147
	v_fma_f32 v94, |v166|, v130, v132
	v_add_f32_e32 v166, v129, v148
	v_fma_f32 v95, |v166|, v130, v132
	s_branch .Ldfa_back_o_d
